# v93 + grid barrier acquire: ONE L2 invalidate per XCD (the XCD leader waits for its buffer_inv sc1 before releasing its workgroups; the other workgroups invalidate only their CU's L1 with buffer_inv s
# speedup vs baseline: 1.0202x; 1.0202x over previous
.LBB0_42:
	s_or_b64 exec, exec, s[14:15]
	s_waitcnt vmcnt(0)
	buffer_inv sc0
	s_waitcnt vmcnt(0)

.LBB0_60:
	s_or_b64 exec, exec, s[4:5]
	s_mov_b64 s[4:5], exec
	v_mbcnt_lo_u32_b32 v1, s4, 0
	v_mbcnt_hi_u32_b32 v1, s5, v1
	v_cmp_eq_u32_e32 vcc, 0, v1
	s_waitcnt vmcnt(0)
	buffer_inv sc1
	s_waitcnt vmcnt(0)
	s_and_saveexec_b64 s[12:13], vcc
	s_cbranch_execz .LBB0_62
	s_bcnt1_i32_b64 s4, s[4:5]
	v_mov_b32_e32 v1, 0x2000
	v_mov_b32_e32 v2, s4
	global_atomic_add v1, v2, s[6:7] offset:1024

.LBB0_212:
	s_or_b64 exec, exec, s[6:7]
	s_mov_b64 s[6:7], exec
	v_mbcnt_lo_u32_b32 v1, s6, 0
	v_mbcnt_hi_u32_b32 v1, s7, v1
	v_cmp_eq_u32_e32 vcc, 0, v1
	s_waitcnt vmcnt(0)
	buffer_inv sc1
	s_waitcnt vmcnt(0)
	s_and_saveexec_b64 s[12:13], vcc
	s_cbranch_execz .LBB0_214
	s_bcnt1_i32_b64 s6, s[6:7]
	v_mov_b32_e32 v1, 0x2000
	v_mov_b32_e32 v2, s6
	global_atomic_add v1, v2, s[8:9] offset:1024

.LBB0_277:
	s_or_b64 exec, exec, s[4:5]
	s_mov_b64 s[4:5], exec
	v_mbcnt_lo_u32_b32 v1, s4, 0
	v_mbcnt_hi_u32_b32 v1, s5, v1
	v_cmp_eq_u32_e32 vcc, 0, v1
	s_waitcnt vmcnt(0)
	buffer_inv sc1
	s_waitcnt vmcnt(0)
	s_and_saveexec_b64 s[12:13], vcc
	s_cbranch_execz .LBB0_279
	s_bcnt1_i32_b64 s4, s[4:5]
	v_mov_b32_e32 v1, 0x2000
	v_mov_b32_e32 v2, s4
	global_atomic_add v1, v2, s[8:9] offset:1024

.LBB0_396:
	s_or_b64 exec, exec, s[12:13]
	s_waitcnt vmcnt(0)
	buffer_inv sc0
	s_waitcnt vmcnt(0)

.LBB0_414:
	s_or_b64 exec, exec, s[4:5]
	s_mov_b64 s[4:5], exec
	v_mbcnt_lo_u32_b32 v1, s4, 0
	v_mbcnt_hi_u32_b32 v1, s5, v1
	v_cmp_eq_u32_e32 vcc, 0, v1
	s_waitcnt vmcnt(0)
	buffer_inv sc1
	s_waitcnt vmcnt(0)
	s_and_saveexec_b64 s[8:9], vcc
	s_cbranch_execz .LBB0_416
	s_bcnt1_i32_b64 s4, s[4:5]
	v_mov_b32_e32 v1, 0x2000
	v_mov_b32_e32 v2, s4
	global_atomic_add v1, v2, s[6:7] offset:1024
